# CD: the end-of-call store drain (vmcnt(0)) is deferred to just before the next GEMM call's first LDS-DMA load, overlapping the call-end barriers and scalar set-up
# speedup vs baseline: 1.0006x; 1.0006x over previous
; __device__ __forceinline__ int otid() { int t = threadIdx.x; asm volatile("" : "+v"(t)); return t; }
; #define PG8_WAIT_V(n) asm volatile("s_waitcnt vmcnt(" #n ")" ::: "memory")
; #define PG8_BAR __builtin_amdgcn_s_barrier()
; __device__ __forceinline__ bool gemm_phase(LAS unsigned char* lds, int l, int sub, int gi, bool dry = false) {
;     ...
;     const int tid = otid(), wid = __builtin_amdgcn_readfirstlane(tid >> 6), lane = tid & 63, wr = wid >> 2, wc = wid & 3, fr = lane & 15, fq = lane >> 4;
;     const int K = g.K, nt = K / BK;
;     const bool perm = (g.mode != M_RES);
;     unsigned voffA[2], voffB[2];
; #pragma unroll
;     for (int i = 0; i < 2; ++i) { int R, C; stage_rc(tid * 16 + i * 8192, R, C); const int Rb = perm ? ((R & ~31) + perm32(R & 31)) : R;
;         const int Ra = (g.mode == M_UPC) ? ((R & ~63) + 4 * (R & 15) + ((R >> 4) & 3)) : R;
;         voffA[i] = (unsigned)(Ra * g.lda + C) * 2u; voffB[i] = (unsigned)(Rb * g.ldb + C) * 2u; }
;     const size_t kstep = (size_t)(BK * 2);
;     const size_t hstepA = (size_t)HALF * g.lda * 2, hstepB = (size_t)HALF * g.ldb * 2;
;     const size_t tstepA = 2 * hstepA, tstepB = 2 * hstepB;
;     const unsigned ldsw = (unsigned)wid * 1024u;
;     const int aoff = lds_byte(wr * 64 + fr, fq * 8), boff = lds_byte(wc * 32 + fr, fq * 8);
;     ...
;     Unit cur, nxt; int ui = 0;
;     if (!unit_next(g, 0, cur)) return true;
;     f32x4 acc[2][2][4][2];
; #pragma unroll
;     for (int a = 0; a < 2; ++a)
; #pragma unroll
;         for (int b = 0; b < 2; ++b)
; #pragma unroll
;             for (int m = 0; m < 4; ++m)
; #pragma unroll
;                 for (int n = 0; n < 2; ++n) acc[a][b][m][n] = (f32x4){0.f, 0.f, 0.f, 0.f};
;     bf16x8 At[4][2], B0[2][2], B1[2][2];
;     const char* cA = (const char*)g.A + (size_t)cur.pm * tstepA + (size_t)cur.k0 * kstep; const char* cB = (const char*)g.Bt + (size_t)cur.pn * tstepB + (size_t)cur.k0 * kstep;
;     PG8_STAGE(PG8_SB(0, 0), cB, voffB); PG8_STAGE(PG8_SA(0, 0), cA, voffA); PG8_STAGE(PG8_SB(0, 1), cB + hstepB, voffB); PG8_STAGE(PG8_SA(0, 1), cA + hstepA, voffA);
;     if (wr == 1) PG8_BAR;
;     PG8_WAIT_V(4); PG8_BAR;
;     PG8_STAGE(PG8_SB(1, 0), cB + kstep, voffB); PG8_STAGE(PG8_SA(1, 0), cA + kstep, voffA); PG8_STAGE(PG8_SB(1, 1), cB + hstepB + kstep, voffB);
;     PG8_WAIT_V(6); PG8_BAR;
.LBB0_306:
	v_lshlrev_b32_e32 v9, 6, v9
	v_lshlrev_b32_e32 v7, 5, v7
	v_sub_u32_e32 v8, v8, v9
	v_mov_b32_e32 v11, 1
	v_and_b32_e32 v7, 32, v7
	v_ashrrev_i16_sdwa v8, v11, sext(v8) dst_sel:DWORD dst_unused:UNUSED_PAD src0_sel:DWORD src1_sel:BYTE_0
	v_lshlrev_b32_e32 v9, 2, v5
	s_cmp_eq_u32 s8, 6
	v_add_u32_sdwa v7, v7, sext(v8) dst_sel:DWORD dst_unused:UNUSED_PAD src0_sel:DWORD src1_sel:WORD_0
	v_and_b32_e32 v8, 0xffffffc0, v5
	v_and_b32_e32 v9, 60, v9
	v_bfe_u32 v10, v5, 4, 2
	s_cselect_b64 vcc, -1, 0
	v_or3_b32 v8, v9, v8, v10
	v_cndmask_b32_e32 v5, v5, v8, vcc
	v_mul_i32_i24_e32 v3, 64, v3
	v_mul_lo_u32 v5, v5, s0
	v_lshlrev_b32_e32 v0, 5, v0
	v_sub_u32_e32 v2, v2, v3
	v_add_lshl_u32 v216, v5, v7, 1
	v_mul_lo_u32 v5, v6, s0
	v_and_b32_e32 v0, 32, v0
	v_ashrrev_i16_sdwa v2, v11, sext(v2) dst_sel:DWORD dst_unused:UNUSED_PAD src0_sel:DWORD src1_sel:BYTE_0
	v_lshlrev_b32_e32 v3, 2, v1
	v_add_lshl_u32 v218, v5, v7, 1
	v_add_u32_sdwa v0, v0, sext(v2) dst_sel:DWORD dst_unused:UNUSED_PAD src0_sel:DWORD src1_sel:WORD_0
	v_and_b32_e32 v2, 0xffffffc0, v1
	v_and_b32_e32 v3, 60, v3
	v_bfe_u32 v5, v1, 4, 2
	v_or3_b32 v2, v3, v2, v5
	s_ashr_i32 s1, s0, 31
	v_cndmask_b32_e32 v1, v1, v2, vcc
	s_lshl_b64 s[68:69], s[0:1], 9
	v_mul_lo_u32 v1, v1, s0
	s_ashr_i32 s6, s33, 31
	s_ashr_i32 s8, s80, 31
	s_lshl_b64 s[66:67], s[0:1], 8
	v_add_lshl_u32 v220, v1, v0, 1
	v_mul_lo_u32 v1, v4, s0
	s_mul_i32 s6, s68, s6
	s_mul_hi_u32 s7, s68, s33
	s_lshr_b64 s[0:1], s[0:1], 23
	s_mul_i32 s8, s68, s8
	s_mul_hi_u32 s10, s68, s80
	s_ashr_i32 s4, s20, 6
	s_add_i32 s6, s7, s6
	s_mul_i32 s1, s0, s33
	s_add_i32 s8, s10, s8
	s_mul_i32 s0, s0, s80
	s_ashr_i32 s5, s20, 8
	s_lshl_b32 s18, s4, 10
	s_add_i32 s6, s6, s1
	s_lshl_b32 s7, s77, 7
	s_add_i32 s8, s8, s0
	s_mul_i32 s0, s68, s80
	s_add_u32 s0, s60, s0
	s_addc_u32 s8, s61, s8
	s_add_u32 s82, s0, s7
	s_addc_u32 s83, s8, 0
	s_add_i32 s19, s18, 0
	v_add_lshl_u32 v222, v1, v0, 1
	s_waitcnt vmcnt(0)
	s_add_i32 m0, s19, 0x10000
	s_mul_i32 s1, s68, s33
	global_load_lds_dwordx4 v222, s[82:83]
	s_add_i32 m0, s19, 0x12000
	s_add_u32 s0, s56, s1
	s_addc_u32 s1, s57, s6
	s_add_u32 s22, s0, s7
	global_load_lds_dwordx4 v218, s[82:83]
	s_addc_u32 s23, s1, 0
	s_mov_b32 m0, s19
	s_add_i32 s10, s19, 0x2000
	global_load_lds_dwordx4 v220, s[22:23]
	s_mov_b32 m0, s10
	s_add_u32 s0, s82, s66
	global_load_lds_dwordx4 v216, s[22:23]
	s_addc_u32 s1, s83, s67
	s_add_i32 m0, s19, 0x14000
	v_mov_b32_e32 v223, v97
	v_mov_b32_e32 v219, v97
	global_load_lds_dwordx4 v222, s[0:1]
	s_add_i32 m0, s19, 0x16000
	v_lshl_add_u64 v[8:9], s[0:1], 0, v[222:223]
	v_lshl_add_u64 v[10:11], s[0:1], 0, v[218:219]
	global_load_lds_dwordx4 v218, s[0:1]
	s_add_u32 s0, s22, s66
	s_addc_u32 s1, s23, s67
	s_add_i32 s73, s19, 0x4000
	s_mov_b32 m0, s73
	s_add_i32 s31, s19, 0x6000
	global_load_lds_dwordx4 v220, s[0:1]
	s_mov_b32 m0, s31
	v_mov_b32_e32 v221, v97
	global_load_lds_dwordx4 v216, s[0:1]
	v_mov_b32_e32 v217, v97
	v_writelane_b32 v255, s20, 13
	v_lshl_add_u64 v[0:1], s[82:83], 0, v[222:223]
	v_lshl_add_u64 v[2:3], s[82:83], 0, v[218:219]
	v_lshl_add_u64 v[4:5], s[22:23], 0, v[220:221]
	v_lshl_add_u64 v[6:7], s[22:23], 0, v[216:217]
	s_cmp_lg_u32 s5, 1
	s_cbranch_scc1 .LBB0_308
	s_barrier

; #define PG8_WAIT_V(n) asm volatile("s_waitcnt vmcnt(" #n ")" ::: "memory")
; #define PG8_BAR __builtin_amdgcn_s_barrier()
; __device__ __forceinline__ bool gemm_phase(LAS unsigned char* lds, int l, int sub, int gi, bool dry = false) {
;     ...
;     PG8_WAIT_V(0);
;     if (wr == 0) PG8_BAR;
;     PG8_BAR;
;     return true;
.LBB0_625:
	v_readlane_b32 s0, v255, 13
	v_readlane_b32 s78, v254, 61
	v_readlane_b32 s36, v254, 55
	s_cmpk_gt_u32 s0, 0xff
	v_readlane_b32 s16, v255, 12
	v_readlane_b32 s74, v254, 59
	v_readlane_b32 s79, v254, 62
	v_readlane_b32 s37, v254, 56
	s_movk_i32 s38, 0xa00
	s_mov_b32 s39, 0xffff0000
	s_movk_i32 s63, 0xff00
	s_movk_i32 s28, 0x6000
	v_mov_b32_e32 v233, 0x358637bd
	v_mov_b32_e32 v234, 0x3e642e9d
	v_mov_b32_e32 v235, 0x204
	v_mov_b32_e32 v238, 0x1f8
	v_mov_b32_e32 v246, 0xbf1f24be
	v_mov_b32_e32 v239, 0x3c0881c4
	v_mov_b32_e32 v241, 0x1600
	v_not_b32_e32 v247, 63
	v_readlane_b32 s75, v254, 60
	s_cbranch_scc1 .LBB0_201
	s_barrier
	s_branch .LBB0_201
